# W_up f32->bf16 conversion items rebalanced: P1 idle tail +6144, GLU idle tail +4096, prologue -10240 (on top of P6 coalesced stores)
# speedup vs baseline: 1.0048x; 1.0048x over previous
.LBB0_49:
	s_and_b64 vcc, exec, s[0:1]
	s_cbranch_vccz .LBB0_55
	s_cmpk_gt_i32 s12, 0x2bff
	s_cbranch_scc1 .LBB0_55
	s_add_i32 s13, s12, 0x8000
	s_mul_hi_i32 s0, s13, 0x2fa0be83
	s_lshr_b32 s1, s0, 31
	s_ashr_i32 s0, s0, 7
	v_readlane_b32 s16, v243, 33
	s_add_i32 s0, s0, s1
	v_lshrrev_b32_e32 v1, 3, v174
	v_readlane_b32 s26, v243, 43
	v_readlane_b32 s27, v243, 44
	s_mul_i32 s1, s0, 0x2b0
	s_waitcnt vmcnt(10)
	v_lshl_or_b32 v4, s0, 6, v1
	s_mov_b32 s2, 0x15800
	v_mov_b64_e32 v[2:3], s[26:27]
	s_sub_i32 s3, s13, s1
	v_mad_i64_i32 v[2:3], s[0:1], v4, s2, v[2:3]
	s_lshl_b32 s0, s3, 5
	v_and_b32_e32 v35, 7, v0
	s_ashr_i32 s1, s0, 31
	v_lshl_add_u64 v[2:3], s[0:1], 2, v[2:3]
	v_mov_b32_e32 v67, 0
	v_lshlrev_b32_e32 v66, 4, v35
	s_waitcnt vmcnt(4)
	v_lshl_add_u64 v[26:27], v[2:3], 0, v[66:67]
	s_mov_b32 s3, 0xac000
	v_add_co_u32_e32 v2, vcc, s3, v26
	s_mov_b32 s4, 0x158000
	s_nop 0
	v_addc_co_u32_e32 v3, vcc, 0, v27, vcc
	v_add_co_u32_e32 v10, vcc, s4, v26
	s_mov_b32 s5, 0x204000
	s_nop 0
	v_addc_co_u32_e32 v11, vcc, 0, v27, vcc
	v_add_co_u32_e32 v12, vcc, s5, v26
	s_mov_b32 s6, 0x2b0000
	s_nop 0
	v_addc_co_u32_e32 v13, vcc, 0, v27, vcc
	v_add_co_u32_e32 v18, vcc, s6, v26
	s_mov_b32 s7, 0x35c000
	s_nop 0
	v_addc_co_u32_e32 v19, vcc, 0, v27, vcc
	v_add_co_u32_e32 v20, vcc, s7, v26
	s_mov_b32 s8, 0x408000
	s_nop 0
	v_addc_co_u32_e32 v21, vcc, 0, v27, vcc
	v_add_co_u32_e32 v28, vcc, s8, v26
	s_mov_b32 s9, 0x4b4000
	s_nop 0
	v_addc_co_u32_e32 v29, vcc, 0, v27, vcc
	global_load_dwordx4 v[6:9], v[26:27], off nt
	s_nop 0
	global_load_dwordx4 v[2:5], v[2:3], off nt
	v_add_co_u32_e32 v26, vcc, s9, v26
	global_load_dwordx4 v[14:17], v[10:11], off nt
	s_nop 0
	global_load_dwordx4 v[10:13], v[12:13], off nt
	v_addc_co_u32_e32 v27, vcc, 0, v27, vcc
	global_load_dwordx4 v[22:25], v[18:19], off nt
	s_nop 0
	global_load_dwordx4 v[18:21], v[20:21], off nt
	s_nop 0
	global_load_dwordx4 v[30:33], v[28:29], off nt
	s_nop 0
	global_load_dwordx4 v[26:29], v[26:27], off nt
	s_lshl_b32 s0, s84, 14
	s_add_i32 s15, s0, 0
	v_lshl_add_u64 v[36:37], s[80:81], 0, v[66:67]
	s_mov_b64 s[0:1], 0x1800000
	v_lshlrev_b32_e32 v34, 2, v35
	v_add_u32_e32 v38, s15, v66
	v_mul_u32_u24_e32 v35, 0x420, v35
	v_lshl_add_u64 v[68:69], v[36:37], 0, s[0:1]
	v_mul_u32_u24_e32 v36, 0x84, v1
	v_lshlrev_b32_e32 v37, 2, v1
	v_or_b32_e32 v70, 8, v1
	v_or_b32_e32 v71, 16, v1
	v_or_b32_e32 v72, 24, v1
	v_add3_u32 v73, s15, v35, v37
	v_lshlrev_b32_e32 v66, 2, v34
	v_add_u32_e32 v74, v38, v36
	v_readlane_b32 s17, v243, 34
	v_readlane_b32 s18, v243, 35
	v_readlane_b32 s19, v243, 36
	v_readlane_b32 s20, v243, 37
	v_readlane_b32 s21, v243, 38
	v_readlane_b32 s22, v243, 39
	v_readlane_b32 s23, v243, 40
	v_readlane_b32 s24, v243, 41
	v_readlane_b32 s25, v243, 42
	v_readlane_b32 s28, v243, 45
	v_readlane_b32 s29, v243, 46
	v_readlane_b32 s30, v243, 47
	v_readlane_b32 s31, v243, 48
	s_branch .LBB0_53

.LBB0_178:
	v_readlane_b32 s8, v243, 49
	v_readlane_b32 s11, v243, 52
	s_bitcmp1_b32 s11, 11
	s_cselect_b64 s[2:3], -1, 0
	s_or_b64 s[0:1], s[2:3], s[0:1]
	s_and_b64 vcc, exec, s[0:1]
	v_readlane_b32 s9, v243, 50
	v_readlane_b32 s10, v243, 51
	s_cbranch_vccnz .LBB0_184
	s_lshl_b32 s0, s94, 3
	s_add_i32 s0, s0, s84
	s_add_i32 s12, s0, 0xfffffae0
	s_cmpk_gt_i32 s12, 0x37ff
	s_cbranch_scc1 .LBB0_184
	s_mul_hi_i32 s0, s12, 0x2fa0be83
	s_lshr_b32 s1, s0, 31
	s_ashr_i32 s0, s0, 7
	v_readlane_b32 s16, v243, 33
	s_add_i32 s0, s0, s1
	v_lshrrev_b32_e32 v1, 3, v174
	v_readlane_b32 s26, v243, 43
	v_readlane_b32 s27, v243, 44
	s_mul_i32 s1, s0, 0x2b0
	s_waitcnt vmcnt(0)
	v_lshl_or_b32 v4, s0, 6, v1
	s_mov_b32 s2, 0x15800
	v_mov_b64_e32 v[2:3], s[26:27]
	s_sub_i32 s3, s12, s1
	v_mad_i64_i32 v[2:3], s[0:1], v4, s2, v[2:3]
	s_lshl_b32 s0, s3, 5
	v_and_b32_e32 v35, 7, v0
	s_ashr_i32 s1, s0, 31
	v_lshl_add_u64 v[2:3], s[0:1], 2, v[2:3]
	v_mov_b32_e32 v67, 0
	v_lshlrev_b32_e32 v66, 4, v35
	v_lshl_add_u64 v[26:27], v[2:3], 0, v[66:67]
	s_mov_b32 s3, 0xac000
	v_add_co_u32_e32 v2, vcc, s3, v26
	s_mov_b32 s4, 0x158000
	s_nop 0
	v_addc_co_u32_e32 v3, vcc, 0, v27, vcc
	v_add_co_u32_e32 v10, vcc, s4, v26
	s_mov_b32 s5, 0x204000
	s_nop 0
	v_addc_co_u32_e32 v11, vcc, 0, v27, vcc
	v_add_co_u32_e32 v12, vcc, s5, v26
	s_mov_b32 s8, 0x2b0000
	s_nop 0
	v_addc_co_u32_e32 v13, vcc, 0, v27, vcc
	v_add_co_u32_e32 v18, vcc, s8, v26
	s_mov_b32 s9, 0x35c000
	s_nop 0
	v_addc_co_u32_e32 v19, vcc, 0, v27, vcc
	v_add_co_u32_e32 v20, vcc, s9, v26
	s_mov_b32 s10, 0x408000
	s_nop 0
	v_addc_co_u32_e32 v21, vcc, 0, v27, vcc
	v_add_co_u32_e32 v28, vcc, s10, v26
	s_mov_b32 s11, 0x4b4000
	s_nop 0
	v_addc_co_u32_e32 v29, vcc, 0, v27, vcc
	global_load_dwordx4 v[6:9], v[26:27], off nt
	s_nop 0
	global_load_dwordx4 v[2:5], v[2:3], off nt
	v_add_co_u32_e32 v26, vcc, s11, v26
	global_load_dwordx4 v[14:17], v[10:11], off nt
	s_nop 0
	global_load_dwordx4 v[10:13], v[12:13], off nt
	v_addc_co_u32_e32 v27, vcc, 0, v27, vcc
	global_load_dwordx4 v[22:25], v[18:19], off nt
	s_nop 0
	global_load_dwordx4 v[18:21], v[20:21], off nt
	s_nop 0
	global_load_dwordx4 v[30:33], v[28:29], off nt
	s_nop 0
	global_load_dwordx4 v[26:29], v[26:27], off nt
	s_lshl_b32 s0, s84, 14
	s_add_i32 s13, s0, 0
	v_lshl_add_u64 v[36:37], s[80:81], 0, v[66:67]
	s_mov_b64 s[0:1], 0x1800000
	v_lshlrev_b32_e32 v34, 2, v35
	v_add_u32_e32 v38, s13, v66
	v_mul_u32_u24_e32 v35, 0x420, v35
	v_lshl_add_u64 v[68:69], v[36:37], 0, s[0:1]
	v_mul_u32_u24_e32 v36, 0x84, v1
	v_lshlrev_b32_e32 v37, 2, v1
	v_or_b32_e32 v70, 8, v1
	v_or_b32_e32 v71, 16, v1
	v_or_b32_e32 v72, 24, v1
	v_add3_u32 v73, s13, v35, v37
	v_lshl_or_b32 v75, s12, 5, v1
	v_lshlrev_b32_e32 v66, 2, v34
	v_add_u32_e32 v74, v38, v36
	v_readlane_b32 s17, v243, 34
	v_readlane_b32 s18, v243, 35
	v_readlane_b32 s19, v243, 36
	v_readlane_b32 s20, v243, 37
	v_readlane_b32 s21, v243, 38
	v_readlane_b32 s22, v243, 39
	v_readlane_b32 s23, v243, 40
	v_readlane_b32 s24, v243, 41
	v_readlane_b32 s25, v243, 42
	v_readlane_b32 s28, v243, 45
	v_readlane_b32 s29, v243, 46
	v_readlane_b32 s30, v243, 47
	v_readlane_b32 s31, v243, 48
	s_branch .LBB0_182
.LBB0_181:
	s_add_i32 s14, s12, 0x5c0
	s_cmpk_gt_i32 s12, 0x323f
	s_cselect_b64 s[0:1], -1, 0
	s_cmpk_lt_i32 s12, 0x3240
	s_cselect_b32 s12, s14, s13
	s_mul_hi_i32 s15, s12, 0x2fa0be83
	s_lshr_b32 s16, s15, 31
	s_ashr_i32 s15, s15, 7
	s_add_i32 s15, s15, s16
	s_mul_i32 s16, s15, 0x2b0
	v_lshl_or_b32 v4, s15, 6, v1
	v_mov_b64_e32 v[2:3], s[46:47]
	s_sub_i32 s12, s12, s16
	v_mad_i64_i32 v[2:3], s[16:17], v4, s2, v[2:3]
	s_lshl_b32 s16, s12, 5
	s_ashr_i32 s17, s16, 31
	v_lshl_add_u64 v[2:3], s[16:17], 2, v[2:3]
	v_lshl_add_u64 v[26:27], v[2:3], 0, v[66:67]
	v_add_co_u32_e32 v2, vcc, s3, v26
	s_mul_hi_i32 s12, s13, 0x2fa0be83
	s_nop 0
	v_addc_co_u32_e32 v3, vcc, 0, v27, vcc
	v_add_co_u32_e32 v10, vcc, s4, v26
	global_load_dwordx4 v[6:9], v[26:27], off nt
	s_nop 0
	global_load_dwordx4 v[2:5], v[2:3], off nt
	v_addc_co_u32_e32 v11, vcc, 0, v27, vcc
	v_add_co_u32_e32 v12, vcc, s5, v26
	s_lshr_b32 s15, s12, 31
	s_nop 0
	v_addc_co_u32_e32 v13, vcc, 0, v27, vcc
	v_add_co_u32_e32 v18, vcc, s8, v26
	global_load_dwordx4 v[14:17], v[10:11], off nt
	s_nop 0
	global_load_dwordx4 v[10:13], v[12:13], off nt
	v_addc_co_u32_e32 v19, vcc, 0, v27, vcc
	v_add_co_u32_e32 v20, vcc, s9, v26
	s_ashr_i32 s12, s12, 7
	s_nop 0
	v_addc_co_u32_e32 v21, vcc, 0, v27, vcc
	v_add_co_u32_e32 v28, vcc, s10, v26
	global_load_dwordx4 v[22:25], v[18:19], off nt
	s_nop 0
	global_load_dwordx4 v[18:21], v[20:21], off nt
	v_addc_co_u32_e32 v29, vcc, 0, v27, vcc
	v_add_co_u32_e32 v26, vcc, s11, v26
	s_add_i32 s12, s12, s15
	s_nop 0
	v_addc_co_u32_e32 v27, vcc, 0, v27, vcc
	global_load_dwordx4 v[30:33], v[28:29], off nt
	s_nop 0
	global_load_dwordx4 v[26:29], v[26:27], off nt
	s_waitcnt vmcnt(19)
	ds_write2_b32 v74, v34, v35 offset1:1
	ds_write2_b32 v74, v36, v37 offset0:2 offset1:3
	s_waitcnt vmcnt(18)
	ds_write2_b32 v76, v38, v39 offset1:1
	ds_write2_b32 v77, v40, v41 offset1:1
	s_waitcnt vmcnt(17)
	ds_write2_b32 v78, v42, v43 offset1:1
	ds_write2_b32 v79, v44, v45 offset1:1
	s_waitcnt vmcnt(16)
	ds_write2_b32 v80, v46, v47 offset1:1
	ds_write2_b32 v81, v48, v49 offset1:1
	s_waitcnt vmcnt(15)
	ds_write2_b32 v82, v50, v51 offset1:1
	ds_write2_b32 v83, v52, v53 offset1:1
	s_waitcnt vmcnt(14)
	ds_write2_b32 v84, v54, v55 offset1:1
	ds_write2_b32 v85, v56, v57 offset1:1
	s_waitcnt vmcnt(13)
	ds_write2_b32 v86, v58, v59 offset1:1
	ds_write2_b32 v87, v60, v61 offset1:1
	s_waitcnt vmcnt(12)
	ds_write2_b32 v88, v62, v63 offset1:1
	ds_write2_b32 v89, v64, v65 offset1:1
	s_waitcnt lgkmcnt(0)
	s_mul_i32 s15, s12, 0x2b0
	s_sub_i32 s13, s13, s15
	ds_read2_b32 v[38:39], v73 offset0:33 offset1:41
	ds_read2_b32 v[40:41], v73 offset1:8
	ds_read2_b32 v[42:43], v73 offset0:66 offset1:74
	ds_read2_b32 v[44:45], v73 offset0:99 offset1:107
	ds_read2_b32 v[46:47], v73 offset0:132 offset1:140
	ds_read2_b32 v[48:49], v73 offset0:165 offset1:173
	ds_read2_b32 v[50:51], v73 offset0:198 offset1:206
	ds_read2_b32 v[52:53], v73 offset0:231 offset1:239
	s_lshl_b32 s15, s13, 5
	s_lshl_b32 s12, s12, 6
	v_or_b32_e32 v56, s15, v1
	s_ashr_i32 s13, s12, 31
	v_ashrrev_i32_e32 v57, 31, v56
	v_lshl_add_u64 v[54:55], s[12:13], 1, v[68:69]
	v_lshlrev_b64 v[56:57], 13, v[56:57]
	s_waitcnt lgkmcnt(6)
	v_cvt_pk_bf16_f32 v34, v40, v38
	s_waitcnt lgkmcnt(4)
	v_cvt_pk_bf16_f32 v35, v42, v44
	s_waitcnt lgkmcnt(2)
	v_cvt_pk_bf16_f32 v36, v46, v48
	s_waitcnt lgkmcnt(0)
	v_cvt_pk_bf16_f32 v37, v50, v52
	v_lshl_add_u64 v[56:57], v[54:55], 0, v[56:57]
	v_or_b32_e32 v38, s15, v70
	global_store_dwordx4 v[56:57], v[34:37], off nt
	v_add_u32_e32 v75, 0xb800, v75
	s_mov_b32 s12, s14
	v_cvt_pk_bf16_f32 v34, v41, v39
	v_ashrrev_i32_e32 v39, 31, v38
	v_cvt_pk_bf16_f32 v35, v43, v45
	v_cvt_pk_bf16_f32 v36, v47, v49
	v_cvt_pk_bf16_f32 v37, v51, v53
	v_lshlrev_b64 v[38:39], 13, v[38:39]
	ds_read2_b32 v[40:41], v73 offset0:49 offset1:57
	ds_read2_b32 v[42:43], v73 offset0:16 offset1:24
	ds_read2_b32 v[44:45], v73 offset0:82 offset1:90
	ds_read2_b32 v[46:47], v73 offset0:115 offset1:123
	ds_read2_b32 v[48:49], v73 offset0:148 offset1:156
	ds_read2_b32 v[50:51], v73 offset0:181 offset1:189
	ds_read2_b32 v[52:53], v73 offset0:214 offset1:222
	ds_read2_b32 v[56:57], v73 offset0:247 offset1:255
	v_lshl_add_u64 v[38:39], v[54:55], 0, v[38:39]
	global_store_dwordx4 v[38:39], v[34:37], off nt
	v_or_b32_e32 v38, s15, v71
	v_ashrrev_i32_e32 v39, 31, v38
	v_lshlrev_b64 v[38:39], 13, v[38:39]
	s_waitcnt lgkmcnt(6)
	v_cvt_pk_bf16_f32 v34, v42, v40
	s_waitcnt lgkmcnt(4)
	v_cvt_pk_bf16_f32 v35, v44, v46
	s_waitcnt lgkmcnt(2)
	v_cvt_pk_bf16_f32 v36, v48, v50
	s_waitcnt lgkmcnt(0)
	v_cvt_pk_bf16_f32 v37, v52, v56
	v_lshl_add_u64 v[38:39], v[54:55], 0, v[38:39]
	global_store_dwordx4 v[38:39], v[34:37], off nt
	v_or_b32_e32 v38, s15, v72
	v_ashrrev_i32_e32 v39, 31, v38
	v_lshlrev_b64 v[38:39], 13, v[38:39]
	v_cvt_pk_bf16_f32 v34, v43, v41
	v_cvt_pk_bf16_f32 v35, v45, v47
	v_cvt_pk_bf16_f32 v36, v49, v51
	v_cvt_pk_bf16_f32 v37, v53, v57
	v_lshl_add_u64 v[38:39], v[54:55], 0, v[38:39]
	global_store_dwordx4 v[38:39], v[34:37], off nt
	s_waitcnt lgkmcnt(0)
	s_andn2_b64 vcc, exec, s[0:1]
	s_cbranch_vccz .LBB0_184
.LBB0_182:
	s_add_i32 s13, s12, 0x2e0
	s_cmpk_lt_i32 s12, 0x3520
	s_cselect_b32 s0, s13, s12
	s_mul_hi_i32 s1, s0, 0x2fa0be83
	s_lshr_b32 s14, s1, 31
	s_ashr_i32 s1, s1, 7
	s_add_i32 s16, s1, s14
	s_mul_i32 s1, s16, 0x2b0
	v_readlane_b32 s36, v243, 33
	s_sub_i32 s0, s0, s1
	v_readlane_b32 s46, v243, 43
	v_readlane_b32 s47, v243, 44
	s_lshl_b32 s14, s0, 5
	s_waitcnt vmcnt(11)
	v_lshl_or_b32 v36, s16, 6, v1
	v_mov_b64_e32 v[34:35], s[46:47]
	s_ashr_i32 s15, s14, 31
	v_mad_i64_i32 v[34:35], s[16:17], v36, s2, v[34:35]
	v_lshl_add_u64 v[34:35], s[14:15], 2, v[34:35]
	s_waitcnt vmcnt(5)
	v_lshl_add_u64 v[58:59], v[34:35], 0, v[66:67]
	v_add_co_u32_e32 v38, vcc, s3, v58
	v_add_u32_e32 v76, 0x420, v74
	s_nop 0
	v_addc_co_u32_e32 v39, vcc, 0, v59, vcc
	v_add_co_u32_e32 v42, vcc, s4, v58
	global_load_dwordx4 v[34:37], v[58:59], off nt
	s_nop 0
	global_load_dwordx4 v[38:41], v[38:39], off nt
	v_addc_co_u32_e32 v43, vcc, 0, v59, vcc
	v_add_co_u32_e32 v46, vcc, s5, v58
	v_add_u32_e32 v77, 0x428, v74
	s_nop 0
	v_addc_co_u32_e32 v47, vcc, 0, v59, vcc
	v_add_co_u32_e32 v50, vcc, s8, v58
	global_load_dwordx4 v[42:45], v[42:43], off nt
	s_nop 0
	global_load_dwordx4 v[46:49], v[46:47], off nt
	v_addc_co_u32_e32 v51, vcc, 0, v59, vcc
	v_add_co_u32_e32 v54, vcc, s9, v58
	v_add_u32_e32 v78, 0x840, v74
	s_nop 0
	v_addc_co_u32_e32 v55, vcc, 0, v59, vcc
	v_add_co_u32_e32 v60, vcc, s10, v58
	global_load_dwordx4 v[50:53], v[50:51], off nt
	s_nop 0
	global_load_dwordx4 v[54:57], v[54:55], off nt
	v_addc_co_u32_e32 v61, vcc, 0, v59, vcc
	s_waitcnt vmcnt(10)
	v_add_co_u32_e32 v62, vcc, s11, v58
	v_add_u32_e32 v79, 0x848, v74
	s_nop 0
	v_addc_co_u32_e32 v63, vcc, 0, v59, vcc
	global_load_dwordx4 v[58:61], v[60:61], off nt
	s_nop 0
	global_load_dwordx4 v[62:65], v[62:63], off nt
	v_add_u32_e32 v80, 0xc60, v74
	v_add_u32_e32 v81, 0xc68, v74
	v_add_u32_e32 v82, 0x1080, v74
	v_add_u32_e32 v83, 0x1088, v74
	v_add_u32_e32 v84, 0x14a0, v74
	v_add_u32_e32 v85, 0x14a8, v74
	v_add_u32_e32 v86, 0x18c0, v74
	v_add_u32_e32 v87, 0x18c8, v74
	v_add_u32_e32 v88, 0x1ce0, v74
	v_add_u32_e32 v89, 0x1ce8, v74
	s_waitcnt vmcnt(15)
	ds_write2_b32 v74, v6, v7 offset1:1
	ds_write2_b32 v74, v8, v9 offset0:2 offset1:3
	s_waitcnt vmcnt(14)
	ds_write2_b32 v76, v2, v3 offset1:1
	ds_write2_b32 v77, v4, v5 offset1:1
	s_waitcnt vmcnt(13)
	ds_write2_b32 v78, v14, v15 offset1:1
	ds_write2_b32 v79, v16, v17 offset1:1
	s_waitcnt vmcnt(12)
	ds_write2_b32 v80, v10, v11 offset1:1
	ds_write2_b32 v81, v12, v13 offset1:1
	s_waitcnt vmcnt(11)
	ds_write2_b32 v82, v22, v23 offset1:1
	ds_write2_b32 v83, v24, v25 offset1:1
	s_waitcnt vmcnt(10)
	ds_write2_b32 v84, v18, v19 offset1:1
	ds_write2_b32 v85, v20, v21 offset1:1
	s_waitcnt vmcnt(9)
	ds_write2_b32 v86, v30, v31 offset1:1
	ds_write2_b32 v87, v32, v33 offset1:1
	s_waitcnt vmcnt(8)
	ds_write2_b32 v88, v26, v27 offset1:1
	ds_write2_b32 v89, v28, v29 offset1:1
	s_mul_hi_i32 s0, s12, 0x2fa0be83
	s_waitcnt lgkmcnt(0)
	s_lshr_b32 s1, s0, 31
	s_ashr_i32 s0, s0, 7
	s_add_i32 s18, s0, s1
	ds_read2_b32 v[6:7], v73 offset0:33 offset1:41
	ds_read2_b32 v[8:9], v73 offset1:8
	ds_read2_b32 v[10:11], v73 offset0:66 offset1:74
	ds_read2_b32 v[12:13], v73 offset0:99 offset1:107
	ds_read2_b32 v[14:15], v73 offset0:132 offset1:140
	ds_read2_b32 v[16:17], v73 offset0:165 offset1:173
	ds_read2_b32 v[18:19], v73 offset0:198 offset1:206
	ds_read2_b32 v[20:21], v73 offset0:231 offset1:239
	s_lshl_b32 s0, s18, 6
	s_mulk_i32 s18, 0xaa00
	v_add_u32_e32 v24, s18, v75
	s_ashr_i32 s1, s0, 31
	v_ashrrev_i32_e32 v25, 31, v24
	v_lshl_add_u64 v[22:23], s[0:1], 1, v[68:69]
	v_lshlrev_b64 v[26:27], 13, v[24:25]
	s_waitcnt lgkmcnt(0)
	v_cvt_pk_bf16_f32 v2, v8, v6
	v_cvt_pk_bf16_f32 v3, v10, v12
	v_cvt_pk_bf16_f32 v4, v14, v16
	v_cvt_pk_bf16_f32 v5, v18, v20
	v_lshl_add_u64 v[26:27], v[22:23], 0, v[26:27]
	v_add_u32_e32 v6, 8, v24
	global_store_dwordx4 v[26:27], v[2:5], off nt
	s_cmpk_gt_i32 s12, 0x351f
	v_readlane_b32 s37, v243, 34
	v_cvt_pk_bf16_f32 v2, v9, v7
	v_ashrrev_i32_e32 v7, 31, v6
	v_cvt_pk_bf16_f32 v3, v11, v13
	v_cvt_pk_bf16_f32 v4, v15, v17
	v_cvt_pk_bf16_f32 v5, v19, v21
	v_lshlrev_b64 v[6:7], 13, v[6:7]
	ds_read2_b32 v[8:9], v73 offset0:49 offset1:57
	ds_read2_b32 v[10:11], v73 offset0:16 offset1:24
	ds_read2_b32 v[12:13], v73 offset0:82 offset1:90
	ds_read2_b32 v[14:15], v73 offset0:115 offset1:123
	ds_read2_b32 v[16:17], v73 offset0:148 offset1:156
	ds_read2_b32 v[18:19], v73 offset0:181 offset1:189
	ds_read2_b32 v[20:21], v73 offset0:214 offset1:222
	ds_read2_b32 v[26:27], v73 offset0:247 offset1:255
	v_lshl_add_u64 v[6:7], v[22:23], 0, v[6:7]
	global_store_dwordx4 v[6:7], v[2:5], off nt
	v_add_u32_e32 v6, 16, v24
	v_ashrrev_i32_e32 v7, 31, v6
	v_lshlrev_b64 v[6:7], 13, v[6:7]
	s_waitcnt lgkmcnt(6)
	v_cvt_pk_bf16_f32 v2, v10, v8
	s_waitcnt lgkmcnt(4)
	v_cvt_pk_bf16_f32 v3, v12, v14
	s_waitcnt lgkmcnt(2)
	v_cvt_pk_bf16_f32 v4, v16, v18
	s_waitcnt lgkmcnt(0)
	v_cvt_pk_bf16_f32 v5, v20, v26
	v_lshl_add_u64 v[6:7], v[22:23], 0, v[6:7]
	global_store_dwordx4 v[6:7], v[2:5], off nt
	v_add_u32_e32 v6, 24, v24
	v_ashrrev_i32_e32 v7, 31, v6
	v_lshlrev_b64 v[6:7], 13, v[6:7]
	v_cvt_pk_bf16_f32 v2, v11, v9
	v_cvt_pk_bf16_f32 v3, v13, v15
	v_cvt_pk_bf16_f32 v4, v17, v19
	v_cvt_pk_bf16_f32 v5, v21, v27
	v_lshl_add_u64 v[6:7], v[22:23], 0, v[6:7]
	global_store_dwordx4 v[6:7], v[2:5], off nt
	s_waitcnt lgkmcnt(0)
	v_readlane_b32 s38, v243, 35
	v_readlane_b32 s39, v243, 36
	v_readlane_b32 s40, v243, 37
	v_readlane_b32 s41, v243, 38
	v_readlane_b32 s42, v243, 39
	v_readlane_b32 s43, v243, 40
	v_readlane_b32 s44, v243, 41
	v_readlane_b32 s45, v243, 42
	v_readlane_b32 s48, v243, 45
	v_readlane_b32 s49, v243, 46
	v_readlane_b32 s50, v243, 47
	v_readlane_b32 s51, v243, 48
	s_cbranch_scc0 .LBB0_181

.LBB0_513:
	v_readlane_b32 s2, v243, 0
	s_cmpk_eq_i32 s2, 0x100
	s_cselect_b64 s[0:1], -1, 0
	s_cmpk_lg_i32 s2, 0x100
	s_cselect_b64 s[2:3], -1, 0
	s_bitcmp1_b32 s91, 5
	s_cselect_b64 s[6:7], -1, 0
	s_or_b64 s[2:3], s[2:3], s[6:7]
	s_cmp_lt_i32 s94, 32
	s_cselect_b64 s[6:7], -1, 0
	s_or_b64 s[2:3], s[6:7], s[2:3]
	s_and_b64 vcc, exec, s[2:3]
	s_cbranch_vccnz .LBB0_519
	s_lshl_b32 s2, s94, 3
	s_add_i32 s2, s2, s84
	s_add_i32 s14, s2, 0x3700
	s_cmpk_gt_i32 s14, 0x7fff
	s_cbranch_scc1 .LBB0_519
	s_mul_hi_i32 s2, s14, 0x2fa0be83
	s_lshr_b32 s3, s2, 31
	s_ashr_i32 s2, s2, 7
	v_readlane_b32 s16, v243, 33
	s_add_i32 s2, s2, s3
	v_lshrrev_b32_e32 v1, 3, v174
	v_readlane_b32 s26, v243, 43
	v_readlane_b32 s27, v243, 44
	s_mul_i32 s3, s2, 0x2b0
	s_waitcnt vmcnt(0)
	v_lshl_or_b32 v4, s2, 6, v1
	s_mov_b32 s6, 0x15800
	v_mov_b64_e32 v[2:3], s[26:27]
	s_sub_i32 s7, s14, s3
	v_mad_i64_i32 v[2:3], s[2:3], v4, s6, v[2:3]
	s_lshl_b32 s2, s7, 5
	v_and_b32_e32 v35, 7, v0
	s_ashr_i32 s3, s2, 31
	v_lshl_add_u64 v[2:3], s[2:3], 2, v[2:3]
	v_mov_b32_e32 v67, 0
	v_lshlrev_b32_e32 v66, 4, v35
	v_lshl_add_u64 v[26:27], v[2:3], 0, v[66:67]
	s_mov_b32 s7, 0xac000
	v_add_co_u32_e32 v10, vcc, s7, v26
	s_mov_b32 s8, 0x158000
	s_nop 0
	v_addc_co_u32_e32 v11, vcc, 0, v27, vcc
	global_load_dwordx4 v[6:9], v[26:27], off nt
	global_load_dwordx4 v[2:5], v[10:11], off nt
	v_add_co_u32_e32 v10, vcc, s8, v26
	s_mov_b32 s9, 0x204000
	s_nop 0
	v_addc_co_u32_e32 v11, vcc, 0, v27, vcc
	v_add_co_u32_e32 v12, vcc, s9, v26
	s_mov_b32 s10, 0x2b0000
	s_nop 0
	v_addc_co_u32_e32 v13, vcc, 0, v27, vcc
	v_add_co_u32_e32 v18, vcc, s10, v26
	s_mov_b32 s11, 0x35c000
	s_nop 0
	v_addc_co_u32_e32 v19, vcc, 0, v27, vcc
	v_add_co_u32_e32 v20, vcc, s11, v26
	s_mov_b32 s12, 0x408000
	s_nop 0
	v_addc_co_u32_e32 v21, vcc, 0, v27, vcc
	v_add_co_u32_e32 v28, vcc, s12, v26
	s_mov_b32 s13, 0x4b4000
	s_nop 0
	v_addc_co_u32_e32 v29, vcc, 0, v27, vcc
	v_add_co_u32_e32 v26, vcc, s13, v26
	global_load_dwordx4 v[14:17], v[10:11], off nt
	s_nop 0
	global_load_dwordx4 v[10:13], v[12:13], off nt
	v_addc_co_u32_e32 v27, vcc, 0, v27, vcc
	global_load_dwordx4 v[22:25], v[18:19], off nt
	s_nop 0
	global_load_dwordx4 v[18:21], v[20:21], off nt
	s_nop 0
	global_load_dwordx4 v[30:33], v[28:29], off nt
	s_nop 0
	global_load_dwordx4 v[26:29], v[26:27], off nt
	s_lshl_b32 s2, s84, 14
	s_add_i32 s15, s2, 0
	v_lshl_add_u64 v[36:37], s[80:81], 0, v[66:67]
	s_mov_b64 s[2:3], 0x1800000
	v_lshlrev_b32_e32 v34, 2, v35
	v_add_u32_e32 v38, s15, v66
	v_mul_u32_u24_e32 v35, 0x420, v35
	v_lshl_add_u64 v[68:69], v[36:37], 0, s[2:3]
	v_mul_u32_u24_e32 v36, 0x84, v1
	v_lshlrev_b32_e32 v37, 2, v1
	v_or_b32_e32 v70, 8, v1
	v_or_b32_e32 v71, 16, v1
	v_or_b32_e32 v72, 24, v1
	v_add3_u32 v73, s15, v35, v37
	v_lshl_or_b32 v75, s14, 5, v1
	v_lshlrev_b32_e32 v66, 2, v34
	v_add_u32_e32 v74, v38, v36
	v_readlane_b32 s17, v243, 34
	v_readlane_b32 s18, v243, 35
	v_readlane_b32 s19, v243, 36
	v_readlane_b32 s20, v243, 37
	v_readlane_b32 s21, v243, 38
	v_readlane_b32 s22, v243, 39
	v_readlane_b32 s23, v243, 40
	v_readlane_b32 s24, v243, 41
	v_readlane_b32 s25, v243, 42
	v_readlane_b32 s28, v243, 45
	v_readlane_b32 s29, v243, 46
	v_readlane_b32 s30, v243, 47
	v_readlane_b32 s31, v243, 48
	s_branch .LBB0_517
.LBB0_516:
	s_add_i32 s16, s14, 0xe00
	s_cmpk_gt_i32 s14, 0x71ff
	s_cselect_b64 s[2:3], -1, 0
	s_cmpk_lt_i32 s14, 0x7200
	s_cselect_b32 s14, s16, s15
	s_mul_hi_i32 s17, s14, 0x2fa0be83
	s_lshr_b32 s18, s17, 31
	s_ashr_i32 s17, s17, 7
	s_add_i32 s17, s17, s18
	s_mul_i32 s18, s17, 0x2b0
	v_lshl_or_b32 v4, s17, 6, v1
	v_mov_b64_e32 v[2:3], s[46:47]
	s_sub_i32 s14, s14, s18
	v_mad_i64_i32 v[2:3], s[18:19], v4, s6, v[2:3]
	s_lshl_b32 s18, s14, 5
	s_ashr_i32 s19, s18, 31
	v_lshl_add_u64 v[2:3], s[18:19], 2, v[2:3]
	v_lshl_add_u64 v[26:27], v[2:3], 0, v[66:67]
	v_add_co_u32_e32 v2, vcc, s7, v26
	s_mul_hi_i32 s14, s15, 0x2fa0be83
	s_nop 0
	v_addc_co_u32_e32 v3, vcc, 0, v27, vcc
	v_add_co_u32_e32 v10, vcc, s8, v26
	global_load_dwordx4 v[6:9], v[26:27], off nt
	s_nop 0
	global_load_dwordx4 v[2:5], v[2:3], off nt
	v_addc_co_u32_e32 v11, vcc, 0, v27, vcc
	v_add_co_u32_e32 v12, vcc, s9, v26
	s_lshr_b32 s17, s14, 31
	s_nop 0
	v_addc_co_u32_e32 v13, vcc, 0, v27, vcc
	v_add_co_u32_e32 v18, vcc, s10, v26
	global_load_dwordx4 v[14:17], v[10:11], off nt
	s_nop 0
	global_load_dwordx4 v[10:13], v[12:13], off nt
	v_addc_co_u32_e32 v19, vcc, 0, v27, vcc
	v_add_co_u32_e32 v20, vcc, s11, v26
	s_ashr_i32 s14, s14, 7
	s_nop 0
	v_addc_co_u32_e32 v21, vcc, 0, v27, vcc
	v_add_co_u32_e32 v28, vcc, s12, v26
	global_load_dwordx4 v[22:25], v[18:19], off nt
	s_nop 0
	global_load_dwordx4 v[18:21], v[20:21], off nt
	v_addc_co_u32_e32 v29, vcc, 0, v27, vcc
	v_add_co_u32_e32 v26, vcc, s13, v26
	s_add_i32 s14, s14, s17
	s_nop 0
	v_addc_co_u32_e32 v27, vcc, 0, v27, vcc
	global_load_dwordx4 v[30:33], v[28:29], off nt
	s_nop 0
	global_load_dwordx4 v[26:29], v[26:27], off nt
	s_waitcnt vmcnt(19)
	ds_write2_b32 v74, v34, v35 offset1:1
	ds_write2_b32 v74, v36, v37 offset0:2 offset1:3
	s_waitcnt vmcnt(18)
	ds_write2_b32 v76, v38, v39 offset1:1
	ds_write2_b32 v77, v40, v41 offset1:1
	s_waitcnt vmcnt(17)
	ds_write2_b32 v78, v42, v43 offset1:1
	ds_write2_b32 v79, v44, v45 offset1:1
	s_waitcnt vmcnt(16)
	ds_write2_b32 v80, v46, v47 offset1:1
	ds_write2_b32 v81, v48, v49 offset1:1
	s_waitcnt vmcnt(15)
	ds_write2_b32 v82, v50, v51 offset1:1
	ds_write2_b32 v83, v52, v53 offset1:1
	s_waitcnt vmcnt(14)
	ds_write2_b32 v84, v54, v55 offset1:1
	ds_write2_b32 v85, v56, v57 offset1:1
	s_waitcnt vmcnt(13)
	ds_write2_b32 v86, v58, v59 offset1:1
	ds_write2_b32 v87, v60, v61 offset1:1
	s_waitcnt vmcnt(12)
	ds_write2_b32 v88, v62, v63 offset1:1
	ds_write2_b32 v89, v64, v65 offset1:1
	s_waitcnt lgkmcnt(0)
	s_mul_i32 s17, s14, 0x2b0
	s_sub_i32 s15, s15, s17
	ds_read2_b32 v[38:39], v73 offset0:33 offset1:41
	ds_read2_b32 v[40:41], v73 offset1:8
	ds_read2_b32 v[42:43], v73 offset0:66 offset1:74
	ds_read2_b32 v[44:45], v73 offset0:99 offset1:107
	ds_read2_b32 v[46:47], v73 offset0:132 offset1:140
	ds_read2_b32 v[48:49], v73 offset0:165 offset1:173
	ds_read2_b32 v[50:51], v73 offset0:198 offset1:206
	ds_read2_b32 v[52:53], v73 offset0:231 offset1:239
	s_lshl_b32 s17, s15, 5
	s_lshl_b32 s14, s14, 6
	v_or_b32_e32 v56, s17, v1
	s_ashr_i32 s15, s14, 31
	v_ashrrev_i32_e32 v57, 31, v56
	v_lshl_add_u64 v[54:55], s[14:15], 1, v[68:69]
	v_lshlrev_b64 v[56:57], 13, v[56:57]
	s_waitcnt lgkmcnt(6)
	v_cvt_pk_bf16_f32 v34, v40, v38
	s_waitcnt lgkmcnt(4)
	v_cvt_pk_bf16_f32 v35, v42, v44
	s_waitcnt lgkmcnt(2)
	v_cvt_pk_bf16_f32 v36, v46, v48
	s_waitcnt lgkmcnt(0)
	v_cvt_pk_bf16_f32 v37, v50, v52
	v_lshl_add_u64 v[56:57], v[54:55], 0, v[56:57]
	v_or_b32_e32 v38, s17, v70
	global_store_dwordx4 v[56:57], v[34:37], off nt
	v_add_u32_e32 v75, 0x1c000, v75
	s_mov_b32 s14, s16
	v_cvt_pk_bf16_f32 v34, v41, v39
	v_ashrrev_i32_e32 v39, 31, v38
	v_cvt_pk_bf16_f32 v35, v43, v45
	v_cvt_pk_bf16_f32 v36, v47, v49
	v_cvt_pk_bf16_f32 v37, v51, v53
	v_lshlrev_b64 v[38:39], 13, v[38:39]
	ds_read2_b32 v[40:41], v73 offset0:49 offset1:57
	ds_read2_b32 v[42:43], v73 offset0:16 offset1:24
	ds_read2_b32 v[44:45], v73 offset0:82 offset1:90
	ds_read2_b32 v[46:47], v73 offset0:115 offset1:123
	ds_read2_b32 v[48:49], v73 offset0:148 offset1:156
	ds_read2_b32 v[50:51], v73 offset0:181 offset1:189
	ds_read2_b32 v[52:53], v73 offset0:214 offset1:222
	ds_read2_b32 v[56:57], v73 offset0:247 offset1:255
	v_lshl_add_u64 v[38:39], v[54:55], 0, v[38:39]
	global_store_dwordx4 v[38:39], v[34:37], off nt
	v_or_b32_e32 v38, s17, v71
	v_ashrrev_i32_e32 v39, 31, v38
	v_lshlrev_b64 v[38:39], 13, v[38:39]
	s_waitcnt lgkmcnt(6)
	v_cvt_pk_bf16_f32 v34, v42, v40
	s_waitcnt lgkmcnt(4)
	v_cvt_pk_bf16_f32 v35, v44, v46
	s_waitcnt lgkmcnt(2)
	v_cvt_pk_bf16_f32 v36, v48, v50
	s_waitcnt lgkmcnt(0)
	v_cvt_pk_bf16_f32 v37, v52, v56
	v_lshl_add_u64 v[38:39], v[54:55], 0, v[38:39]
	global_store_dwordx4 v[38:39], v[34:37], off nt
	v_or_b32_e32 v38, s17, v72
	v_ashrrev_i32_e32 v39, 31, v38
	v_lshlrev_b64 v[38:39], 13, v[38:39]
	v_cvt_pk_bf16_f32 v34, v43, v41
	v_cvt_pk_bf16_f32 v35, v45, v47
	v_cvt_pk_bf16_f32 v36, v49, v51
	v_cvt_pk_bf16_f32 v37, v53, v57
	v_lshl_add_u64 v[38:39], v[54:55], 0, v[38:39]
	global_store_dwordx4 v[38:39], v[34:37], off nt
	s_waitcnt lgkmcnt(0)
	s_andn2_b64 vcc, exec, s[2:3]
	s_cbranch_vccz .LBB0_519
.LBB0_517:
	s_add_i32 s15, s14, 0x700
	s_cmpk_lt_i32 s14, 0x7900
	s_cselect_b32 s2, s15, s14
	s_mul_hi_i32 s3, s2, 0x2fa0be83
	s_lshr_b32 s16, s3, 31
	s_ashr_i32 s3, s3, 7
	s_add_i32 s18, s3, s16
	s_mul_i32 s3, s18, 0x2b0
	v_readlane_b32 s36, v243, 33
	s_sub_i32 s2, s2, s3
	v_readlane_b32 s46, v243, 43
	v_readlane_b32 s47, v243, 44
	s_lshl_b32 s16, s2, 5
	s_waitcnt vmcnt(11)
	v_lshl_or_b32 v36, s18, 6, v1
	v_mov_b64_e32 v[34:35], s[46:47]
	s_ashr_i32 s17, s16, 31
	v_mad_i64_i32 v[34:35], s[18:19], v36, s6, v[34:35]
	v_lshl_add_u64 v[34:35], s[16:17], 2, v[34:35]
	s_waitcnt vmcnt(5)
	v_lshl_add_u64 v[58:59], v[34:35], 0, v[66:67]
	v_add_co_u32_e32 v38, vcc, s7, v58
	v_add_u32_e32 v76, 0x420, v74
	s_nop 0
	v_addc_co_u32_e32 v39, vcc, 0, v59, vcc
	v_add_co_u32_e32 v42, vcc, s8, v58
	global_load_dwordx4 v[34:37], v[58:59], off nt
	s_nop 0
	global_load_dwordx4 v[38:41], v[38:39], off nt
	v_addc_co_u32_e32 v43, vcc, 0, v59, vcc
	v_add_co_u32_e32 v46, vcc, s9, v58
	v_add_u32_e32 v77, 0x428, v74
	s_nop 0
	v_addc_co_u32_e32 v47, vcc, 0, v59, vcc
	v_add_co_u32_e32 v50, vcc, s10, v58
	global_load_dwordx4 v[42:45], v[42:43], off nt
	s_nop 0
	global_load_dwordx4 v[46:49], v[46:47], off nt
	v_addc_co_u32_e32 v51, vcc, 0, v59, vcc
	v_add_co_u32_e32 v54, vcc, s11, v58
	v_add_u32_e32 v78, 0x840, v74
	s_nop 0
	v_addc_co_u32_e32 v55, vcc, 0, v59, vcc
	v_add_co_u32_e32 v60, vcc, s12, v58
	global_load_dwordx4 v[50:53], v[50:51], off nt
	s_nop 0
	global_load_dwordx4 v[54:57], v[54:55], off nt
	v_addc_co_u32_e32 v61, vcc, 0, v59, vcc
	s_waitcnt vmcnt(10)
	v_add_co_u32_e32 v62, vcc, s13, v58
	v_add_u32_e32 v79, 0x848, v74
	s_nop 0
	v_addc_co_u32_e32 v63, vcc, 0, v59, vcc
	global_load_dwordx4 v[58:61], v[60:61], off nt
	s_nop 0
	global_load_dwordx4 v[62:65], v[62:63], off nt
	v_add_u32_e32 v80, 0xc60, v74
	v_add_u32_e32 v81, 0xc68, v74
	v_add_u32_e32 v82, 0x1080, v74
	v_add_u32_e32 v83, 0x1088, v74
	v_add_u32_e32 v84, 0x14a0, v74
	v_add_u32_e32 v85, 0x14a8, v74
	v_add_u32_e32 v86, 0x18c0, v74
	v_add_u32_e32 v87, 0x18c8, v74
	v_add_u32_e32 v88, 0x1ce0, v74
	v_add_u32_e32 v89, 0x1ce8, v74
	s_waitcnt vmcnt(15)
	ds_write2_b32 v74, v6, v7 offset1:1
	ds_write2_b32 v74, v8, v9 offset0:2 offset1:3
	s_waitcnt vmcnt(14)
	ds_write2_b32 v76, v2, v3 offset1:1
	ds_write2_b32 v77, v4, v5 offset1:1
	s_waitcnt vmcnt(13)
	ds_write2_b32 v78, v14, v15 offset1:1
	ds_write2_b32 v79, v16, v17 offset1:1
	s_waitcnt vmcnt(12)
	ds_write2_b32 v80, v10, v11 offset1:1
	ds_write2_b32 v81, v12, v13 offset1:1
	s_waitcnt vmcnt(11)
	ds_write2_b32 v82, v22, v23 offset1:1
	ds_write2_b32 v83, v24, v25 offset1:1
	s_waitcnt vmcnt(10)
	ds_write2_b32 v84, v18, v19 offset1:1
	ds_write2_b32 v85, v20, v21 offset1:1
	s_waitcnt vmcnt(9)
	ds_write2_b32 v86, v30, v31 offset1:1
	ds_write2_b32 v87, v32, v33 offset1:1
	s_waitcnt vmcnt(8)
	ds_write2_b32 v88, v26, v27 offset1:1
	ds_write2_b32 v89, v28, v29 offset1:1
	s_mul_hi_i32 s2, s14, 0x2fa0be83
	s_waitcnt lgkmcnt(0)
	s_lshr_b32 s3, s2, 31
	s_ashr_i32 s2, s2, 7
	s_add_i32 s20, s2, s3
	ds_read2_b32 v[6:7], v73 offset0:33 offset1:41
	ds_read2_b32 v[8:9], v73 offset1:8
	ds_read2_b32 v[10:11], v73 offset0:66 offset1:74
	ds_read2_b32 v[12:13], v73 offset0:99 offset1:107
	ds_read2_b32 v[14:15], v73 offset0:132 offset1:140
	ds_read2_b32 v[16:17], v73 offset0:165 offset1:173
	ds_read2_b32 v[18:19], v73 offset0:198 offset1:206
	ds_read2_b32 v[20:21], v73 offset0:231 offset1:239
	s_lshl_b32 s2, s20, 6
	s_mulk_i32 s20, 0xaa00
	v_add_u32_e32 v24, s20, v75
	s_ashr_i32 s3, s2, 31
	v_ashrrev_i32_e32 v25, 31, v24
	v_lshl_add_u64 v[22:23], s[2:3], 1, v[68:69]
	v_lshlrev_b64 v[26:27], 13, v[24:25]
	s_waitcnt lgkmcnt(6)
	v_cvt_pk_bf16_f32 v2, v8, v6
	s_waitcnt lgkmcnt(4)
	v_cvt_pk_bf16_f32 v3, v10, v12
	s_waitcnt lgkmcnt(2)
	v_cvt_pk_bf16_f32 v4, v14, v16
	s_waitcnt lgkmcnt(0)
	v_cvt_pk_bf16_f32 v5, v18, v20
	v_lshl_add_u64 v[26:27], v[22:23], 0, v[26:27]
	v_add_u32_e32 v6, 8, v24
	global_store_dwordx4 v[26:27], v[2:5], off nt
	s_cmpk_gt_i32 s14, 0x78ff
	v_readlane_b32 s37, v243, 34
	v_cvt_pk_bf16_f32 v2, v9, v7
	v_ashrrev_i32_e32 v7, 31, v6
	v_cvt_pk_bf16_f32 v3, v11, v13
	v_cvt_pk_bf16_f32 v4, v15, v17
	v_cvt_pk_bf16_f32 v5, v19, v21
	v_lshlrev_b64 v[6:7], 13, v[6:7]
	ds_read2_b32 v[8:9], v73 offset0:49 offset1:57
	ds_read2_b32 v[10:11], v73 offset0:16 offset1:24
	ds_read2_b32 v[12:13], v73 offset0:82 offset1:90
	ds_read2_b32 v[14:15], v73 offset0:115 offset1:123
	ds_read2_b32 v[16:17], v73 offset0:148 offset1:156
	ds_read2_b32 v[18:19], v73 offset0:181 offset1:189
	ds_read2_b32 v[20:21], v73 offset0:214 offset1:222
	ds_read2_b32 v[26:27], v73 offset0:247 offset1:255
	v_lshl_add_u64 v[6:7], v[22:23], 0, v[6:7]
	global_store_dwordx4 v[6:7], v[2:5], off nt
	v_add_u32_e32 v6, 16, v24
	v_ashrrev_i32_e32 v7, 31, v6
	v_lshlrev_b64 v[6:7], 13, v[6:7]
	s_waitcnt lgkmcnt(6)
	v_cvt_pk_bf16_f32 v2, v10, v8
	s_waitcnt lgkmcnt(4)
	v_cvt_pk_bf16_f32 v3, v12, v14
	s_waitcnt lgkmcnt(2)
	v_cvt_pk_bf16_f32 v4, v16, v18
	s_waitcnt lgkmcnt(0)
	v_cvt_pk_bf16_f32 v5, v20, v26
	v_lshl_add_u64 v[6:7], v[22:23], 0, v[6:7]
	global_store_dwordx4 v[6:7], v[2:5], off nt
	v_add_u32_e32 v6, 24, v24
	v_ashrrev_i32_e32 v7, 31, v6
	v_lshlrev_b64 v[6:7], 13, v[6:7]
	v_cvt_pk_bf16_f32 v2, v11, v9
	v_cvt_pk_bf16_f32 v3, v13, v15
	v_cvt_pk_bf16_f32 v4, v17, v19
	v_cvt_pk_bf16_f32 v5, v21, v27
	v_lshl_add_u64 v[6:7], v[22:23], 0, v[6:7]
	global_store_dwordx4 v[6:7], v[2:5], off nt
	s_waitcnt lgkmcnt(0)
	v_readlane_b32 s38, v243, 35
	v_readlane_b32 s39, v243, 36
	v_readlane_b32 s40, v243, 37
	v_readlane_b32 s41, v243, 38
	v_readlane_b32 s42, v243, 39
	v_readlane_b32 s43, v243, 40
	v_readlane_b32 s44, v243, 41
	v_readlane_b32 s45, v243, 42
	v_readlane_b32 s48, v243, 45
	v_readlane_b32 s49, v243, 46
	v_readlane_b32 s50, v243, 47
	v_readlane_b32 s51, v243, 48
	s_cbranch_scc0 .LBB0_516
